# phase-4 work queue hands out the long-sequence attention items before the (now shorter) hyena items: longest-first order for the 16384-token group
# speedup vs baseline: 1.1601x; 1.0090x over previous
; DI int otid() { int t = (int)__builtin_amdgcn_workitem_id_x(); asm volatile("" : "+v"(t)); return t; }
; DI void attn_item(const Ctx& c, int item) {
;   const int tid = otid(), lane = tid & 63, w = tid >> 6;
;   const int L = c.L, nqt = L >> 8;
;   const int lq = c.logL - 8; const int qt = item & (nqt - 1), h = (item >> lq) & 3, seq = item >> (lq + 2);
;   constexpr int KSZ = 64 * 200, VSZ = 128 * 72;
;   bf16* Ks = (bf16*)c.smem;
;   bf16* Vs = Ks + 2 * KSZ;
;   const bf16* Q = (const bf16*)(c.ws + OFF_Q); const bf16* Kb = (const bf16*)(c.ws + OFF_K); const bf16* Vt = (const bf16*)(c.ws + OFF_VT);
;   bf16* Og = (bf16*)(c.ws + OFF_OMLA);
;   const int r32 = lane & 31, hh = lane >> 5;
;   const int tq0 = seq * L + qt * 256 + w * 32;
;   bf16x8 bq[12];
; #pragma unroll
;   for (int ks = 0; ks < 12; ++ks) bq[ks] = *(const bf16x8*)(Q + (size_t)(tq0 + r32) * 768 + h * 192 + ks * 16 + 8 * hh);
;   float m_ = -1e30f, l_ = 0.f;
;   f32x16 oacc[4];
; #pragma unroll
;   for (int dt = 0; dt < 4; ++dt)
; #pragma unroll
;     for (int i = 0; i < 16; ++i) oacc[dt][i] = 0.f;
;   const float sc = 0.07216878364870322f * 1.4426950408889634f;
;   const bf16* Kg = Kb + (size_t)seq * L * 768 + h * 192;
;   const bf16* Vg = Vt + (size_t)(seq * 4 + h) * 128 * L;
;   int krow[3], kseg[3];
; #pragma unroll
;   for (int r = 0; r < 3; ++r) { const int idx = tid + NTHR * r; krow[r] = idx / 24; kseg[r] = (idx % 24) * 8; }
;   const int vrow0 = tid >> 3, vseg = (tid & 7) * 8;
;   const int vpos = (vseg & 48) + ((vseg >> 3) & 1) * 4;
;   u32x4 rk[3], rv[2];
;   const int ntile = L >> 6;
;     ...
;   __syncthreads();
; extern "C" __global__ void __launch_bounds__(NTHR) mega(Params p) {
;     ...
;           __syncthreads();
;           if (otid() == 0) s_item = atomicAdd(my, 1);
;           __syncthreads();
;           const int it = s_item;
;           if (it >= total) break;
;           if (it < n_scan) gdn_scan_item(c, it);
;           else {
;             const int i2 = it - n_scan;
;             if (i2 < n_hy) hyena_item(c, i2, s_red); else attn_item(c, i2 - n_hy);
.LBB0_543:
	s_or_b64 exec, exec, s[0:1]
	s_waitcnt lgkmcnt(0)
	s_barrier
	ds_read_b32 v0, v1 offset:64
	v_readlane_b32 s0, v227, 56
	s_waitcnt lgkmcnt(0)
	v_readfirstlane_b32 s13, v0
	v_cmp_le_i32_e32 vcc, s0, v0
	s_mov_b64 s[0:1], -1
	s_cbranch_vccnz .LBB0_538
	v_readlane_b32 s0, v227, 55
	s_cmp_ge_i32 s13, s0
	s_mov_b64 s[0:1], -1
	s_cbranch_scc0 .LBB0_761
	v_readlane_b32 s0, v227, 55
	s_sub_i32 s90, s13, s0
	s_cmp_eq_u32 s87, 14
	s_cselect_b32 s4, 0x200, 0
	s_xor_b32 s90, s90, s4
	v_readlane_b32 s36, v228, 46
	s_cmpk_gt_i32 s90, 0x1ff
	s_mov_b64 s[0:1], -1
	v_readlane_b32 s37, v228, 47
	s_movk_i32 s35, 0xfe00
	s_movk_i32 s11, 0xdff
	s_movk_i32 s28, 0x5ff
	s_cbranch_scc0 .LBB0_556
	s_add_i32 s0, s90, 0xfffffe00
	v_readlane_b32 s4, v227, 58
	s_lshr_b32 s4, s0, s4
	v_readlane_b32 s1, v227, 59
	s_and_b32 s6, s4, 3
	v_readlane_b32 s4, v227, 53
	s_and_b32 s1, s0, s1
	s_lshr_b32 s4, s0, s4
	v_mov_b32_e32 v40, v186
	s_lshl_b32 s0, s4, s87
	s_lshl_b32 s1, s1, 8
	s_add_i32 s0, s0, s1
	v_and_b32_e32 v41, 31, v40
	v_ashrrev_i32_e32 v0, 1, v40
	v_or_b32_e32 v2, s0, v41
	v_readlane_b32 s0, v228, 12
	v_and_b32_e32 v0, 0xffffffe0, v0
	v_readlane_b32 s1, v228, 13
	v_add_u32_e32 v166, v2, v0
	s_movk_i32 s10, 0x600
	v_mov_b64_e32 v[2:3], s[0:1]
	v_mad_i64_i32 v[2:3], s[0:1], v166, s10, v[2:3]
	v_readlane_b32 s0, v227, 60
	v_bfe_u32 v202, v40, 5, 1
	s_mul_i32 s82, s6, 0x180
	s_mul_hi_u32 s7, s0, s4
	s_mul_i32 s8, s0, s4
	s_lshl_b32 s0, s4, 2
	v_lshl_add_u64 v[2:3], v[2:3], 0, s[82:83]
	v_lshlrev_b32_e32 v0, 4, v202
	s_or_b32 s0, s0, s6
	s_mov_b32 s1, s83
	v_readlane_b32 s4, v227, 61
	v_lshl_add_u64 v[2:3], v[2:3], 0, v[0:1]
	s_lshl_b64 s[4:5], s[0:1], s4
	s_mov_b32 s0, 0x2aaaaaab
	global_load_dwordx4 v[98:101], v[2:3], off
	global_load_dwordx4 v[102:105], v[2:3], off offset:32
	global_load_dwordx4 v[106:109], v[2:3], off offset:64
	global_load_dwordx4 v[110:113], v[2:3], off offset:96
	global_load_dwordx4 v[114:117], v[2:3], off offset:128
	global_load_dwordx4 v[118:121], v[2:3], off offset:160
	global_load_dwordx4 v[122:125], v[2:3], off offset:192
	global_load_dwordx4 v[126:129], v[2:3], off offset:224
	global_load_dwordx4 v[130:133], v[2:3], off offset:256
	global_load_dwordx4 v[134:137], v[2:3], off offset:288
	global_load_dwordx4 v[138:141], v[2:3], off offset:320
	global_load_dwordx4 v[142:145], v[2:3], off offset:352
	v_mul_hi_i32 v2, v40, s0
	v_lshrrev_b32_e32 v3, 31, v2
	v_ashrrev_i32_e32 v2, 2, v2
	v_add_u32_e32 v203, v2, v3
	v_mul_lo_u32 v2, v203, 24
	v_sub_u32_e32 v42, v40, v2
	v_add_u32_e32 v2, 0x200, v40
	v_mul_hi_i32 v3, v2, s0
	v_lshrrev_b32_e32 v4, 31, v3
	v_ashrrev_i32_e32 v3, 2, v3
	v_add_u32_e32 v204, v3, v4
	v_mul_lo_u32 v3, v204, 24
	v_sub_u32_e32 v43, v2, v3
	v_add_u32_e32 v2, 0x400, v40
	v_mul_hi_i32 v3, v2, s0
	v_readlane_b32 s0, v228, 14
	s_add_u32 s0, s0, s8
	v_readlane_b32 s1, v228, 15
	s_addc_u32 s1, s1, s7
	v_lshrrev_b32_e32 v4, 31, v3
	v_ashrrev_i32_e32 v3, 2, v3
	s_add_u32 s0, s0, s82
	v_lshlrev_b32_e32 v168, 3, v42
	v_lshlrev_b32_e32 v170, 3, v43
	v_add_u32_e32 v205, v3, v4
	s_addc_u32 s1, s1, 0
	s_lshl_b64 s[4:5], s[4:5], 1
	v_readlane_b32 s8, v228, 16
	v_mul_lo_u32 v3, v205, 24
	v_readlane_b32 s9, v228, 17
	s_add_u32 s4, s8, s4
	v_mov_b64_e32 v[22:23], s[0:1]
	v_ashrrev_i32_e32 v169, 31, v168
	v_ashrrev_i32_e32 v171, 31, v170
	v_sub_u32_e32 v44, v2, v3
	s_addc_u32 s5, s9, s5
	v_mad_i64_i32 v[2:3], s[8:9], v203, s10, v[22:23]
	v_lshlrev_b64 v[24:25], 1, v[168:169]
	v_mad_i64_i32 v[4:5], s[8:9], v204, s10, v[22:23]
	v_lshlrev_b64 v[26:27], 1, v[170:171]
	v_lshl_add_u64 v[2:3], v[2:3], 0, v[24:25]
	v_lshl_add_u64 v[6:7], v[4:5], 0, v[26:27]
	s_waitcnt vmcnt(63) expcnt(7) lgkmcnt(15)
	s_barrier
; #define ATT_LOAD(KT)                                                                                    \
;   { _Pragma("unroll") for (int r = 0; r < 3; ++r) rk[r] = *(const u32x4*)(Kg + (size_t)((KT) * 64 + krow[r]) * 768 + kseg[r]); \
;     _Pragma("unroll") for (int r = 0; r < 2; ++r) rv[r] = *(const u32x4*)(Vg + (size_t)(vrow0 + 64 * r) * L + (KT) * 64 + vseg); }
; DI void attn_item(const Ctx& c, int item) {
;     ...
;   __syncthreads();
;   ATT_LOAD(0)
;   ATT_STORE(0)
;   if (ntile > 1) ATT_LOAD(1)
;   __syncthreads();
	global_load_dwordx4 v[2:5], v[2:3], off
	s_nop 0
	global_load_dwordx4 v[6:9], v[6:7], off
	v_lshlrev_b32_e32 v172, 3, v44
	v_ashrrev_i32_e32 v173, 31, v172
	v_mad_i64_i32 v[10:11], s[8:9], v205, s10, v[22:23]
	v_lshlrev_b64 v[28:29], 1, v[172:173]
	v_lshl_add_u64 v[10:11], v[10:11], 0, v[28:29]
	v_ashrrev_i32_e32 v30, 3, v40
	global_load_dwordx4 v[10:13], v[10:11], off
	v_lshlrev_b32_e32 v45, 4, v40
	v_ashrrev_i32_e32 v31, 31, v30
	v_add_u32_e32 v18, 64, v30
	v_and_b32_e32 v32, 0x70, v45
	v_mov_b32_e32 v33, v1
	v_lshlrev_b64 v[176:177], s87, v[30:31]
	v_ashrrev_i32_e32 v19, 31, v18
	v_lshl_add_u64 v[174:175], s[4:5], 0, v[32:33]
	v_lshlrev_b64 v[34:35], 1, v[176:177]
	v_lshlrev_b64 v[178:179], s87, v[18:19]
	v_lshl_add_u64 v[14:15], v[174:175], 0, v[34:35]
	v_lshlrev_b64 v[36:37], 1, v[178:179]
	global_load_dwordx4 v[14:17], v[14:15], off
	v_lshl_add_u64 v[18:19], v[174:175], 0, v[36:37]
	v_add_u32_e32 v31, 64, v203
	global_load_dwordx4 v[18:21], v[18:19], off
	v_mad_i64_i32 v[38:39], s[8:9], v31, s10, v[22:23]
	v_lshl_add_u64 v[38:39], v[38:39], 0, v[24:25]
	v_add_u32_e32 v31, 64, v204
	global_load_dwordx4 v[146:149], v[38:39], off
	v_mad_i64_i32 v[38:39], s[8:9], v31, s10, v[22:23]
	v_add_u32_e32 v31, 64, v205
	v_mad_i64_i32 v[22:23], s[8:9], v31, s10, v[22:23]
	v_lshl_add_u64 v[38:39], v[38:39], 0, v[26:27]
	v_lshl_add_u64 v[22:23], v[22:23], 0, v[28:29]
	global_load_dwordx4 v[150:153], v[38:39], off
	global_load_dwordx4 v[154:157], v[22:23], off
	v_lshl_add_u64 v[22:23], s[4:5], 0, v[34:35]
	v_lshl_add_u64 v[22:23], v[22:23], 0, v[32:33]
	v_lshl_add_u64 v[34:35], s[4:5], 0, v[36:37]
	v_lshl_add_u64 v[32:33], v[34:35], 0, v[32:33]
	global_load_dwordx4 v[158:161], v[22:23], off offset:128
	global_load_dwordx4 v[162:165], v[32:33], off offset:128
	s_movk_i32 s5, 0xc8
	v_mul_lo_u32 v23, v203, s5
	v_lshlrev_b32_e32 v169, 1, v23
	v_lshlrev_b32_e32 v23, 4, v42
	s_movk_i32 s4, 0x50
	v_add3_u32 v23, s4, v169, v23
	v_lshlrev_b32_e32 v22, 3, v40
	v_add_u32_e32 v0, 0x50, v0
	v_lshl_add_u64 v[180:181], s[0:1], 0, v[24:25]
	v_lshl_add_u64 v[182:183], s[0:1], 0, v[26:27]
	v_lshl_add_u64 v[184:185], s[0:1], 0, v[28:29]
	v_ashrrev_i32_e32 v167, 31, v166
	v_mov_b32_e32 v211, 0xf149f2ca
	v_mov_b32_e32 v210, 0
	s_movk_i32 s82, 0x80
	s_mov_b32 s7, 0x3dd53b94
	v_readlane_b32 s8, v227, 51
	s_waitcnt vmcnt(9)
	ds_write_b128 v23, v[2:5]
	v_mul_lo_u32 v2, v204, s5
	v_lshlrev_b32_e32 v171, 1, v2
	v_lshlrev_b32_e32 v2, 4, v43
	v_add3_u32 v2, s4, v171, v2
	s_waitcnt vmcnt(8)
	ds_write_b128 v2, v[6:9]
	v_mul_lo_u32 v2, v205, s5
	v_lshlrev_b32_e32 v173, 1, v2
	v_lshlrev_b32_e32 v2, 4, v44
	v_add3_u32 v2, s4, v173, v2
	s_waitcnt vmcnt(7)
	ds_write_b128 v2, v[10:13]
	v_and_b32_e32 v2, 0x60, v45
	s_movk_i32 s4, 0x90
	v_add_u32_e32 v2, 0x50, v2
	v_and_b32_e32 v3, 8, v22
	v_mul_lo_u32 v4, v30, s4
	v_add3_u32 v206, v2, v3, v4
	v_add_u32_e32 v2, 0xc800, v206
	v_and_b32_e32 v3, 64, v189
	v_add_u32_e32 v3, 64, v3
	v_mov_b32_e32 v4, v1
	v_mov_b32_e32 v5, v1
	s_waitcnt vmcnt(6)
	ds_write2_b64 v2, v[14:15], v[16:17] offset1:2
	v_add_u32_e32 v2, 0xe800, v206
	v_mov_b32_e32 v14, v1
	s_waitcnt vmcnt(5)
	ds_write2_b64 v2, v[18:19], v[20:21] offset0:128 offset1:130
	v_xor_b32_e32 v2, 32, v189
	v_cmp_lt_i32_e32 vcc, v2, v3
	v_mul_u32_u24_e32 v3, 0x48, v41
	v_mov_b32_e32 v15, v1
	v_cndmask_b32_e32 v2, v189, v2, vcc
	v_lshlrev_b32_e32 v207, 2, v2
	v_mul_u32_u24_e32 v2, 0xc8, v41
	v_lshl_add_u32 v208, v2, 1, v0
	v_lshl_add_u32 v209, v3, 1, v0
	v_mov_b32_e32 v0, v1
	v_mov_b32_e32 v2, v1
	v_mov_b32_e32 v3, v1
	v_mov_b32_e32 v6, v1
	v_mov_b32_e32 v7, v1
	v_mov_b32_e32 v8, v1
	v_mov_b32_e32 v9, v1
	v_mov_b32_e32 v10, v1
	v_mov_b32_e32 v11, v1
	v_mov_b32_e32 v12, v1
	v_mov_b32_e32 v13, v1
	v_mov_b64_e32 v[64:65], v[14:15]
	v_mov_b64_e32 v[48:49], v[14:15]
	v_mov_b64_e32 v[32:33], v[14:15]
	v_mov_b64_e32 v[62:63], v[12:13]
	v_mov_b64_e32 v[60:61], v[10:11]
	v_mov_b64_e32 v[58:59], v[8:9]
	v_mov_b64_e32 v[56:57], v[6:7]
	v_mov_b64_e32 v[54:55], v[4:5]
	v_mov_b64_e32 v[52:53], v[2:3]
	v_mov_b64_e32 v[50:51], v[0:1]
	v_mov_b64_e32 v[46:47], v[12:13]
	v_mov_b64_e32 v[44:45], v[10:11]
	v_mov_b64_e32 v[42:43], v[8:9]
	v_mov_b64_e32 v[40:41], v[6:7]
	v_mov_b64_e32 v[38:39], v[4:5]
	v_mov_b64_e32 v[36:37], v[2:3]
	v_mov_b64_e32 v[34:35], v[0:1]
	v_mov_b64_e32 v[30:31], v[12:13]
	v_mov_b64_e32 v[28:29], v[10:11]
	v_mov_b64_e32 v[26:27], v[8:9]
	v_mov_b64_e32 v[24:25], v[6:7]
	v_mov_b64_e32 v[22:23], v[4:5]
	v_mov_b64_e32 v[20:21], v[2:3]
	v_mov_b64_e32 v[18:19], v[0:1]
	v_mov_b64_e32 v[16:17], v[14:15]
	s_mov_b32 s4, 0
	v_mov_b64_e32 v[14:15], v[12:13]
	v_mov_b64_e32 v[12:13], v[10:11]
	v_mov_b64_e32 v[10:11], v[8:9]
	v_mov_b64_e32 v[8:9], v[6:7]
	v_mov_b64_e32 v[6:7], v[4:5]
	v_mov_b64_e32 v[4:5], v[2:3]
	v_mov_b64_e32 v[2:3], v[0:1]
	s_waitcnt lgkmcnt(0)
	s_barrier
